# v027 + XCD de-correlation: after the post-F3 chip-wide barrier XCD x sleeps x*1us so the XCDs' epilogue bursts do not collide
# baseline (speedup 1.0000x reference)
.LBB0_757:
	s_or_b64 exec, exec, s[4:5]
	v_readlane_b32 s56, v254, 50
	v_readlane_b32 s4, v254, 39
	v_readlane_b32 s57, v254, 51
	s_waitcnt lgkmcnt(0)
	v_mov_b32_e32 v2, v0
	v_readlane_b32 s5, v254, 40
	s_barrier
	v_readlane_b32 s100, v255, 4
	s_nop 3
	s_and_b32 s100, s100, 7
.Lstg_loop1:
	s_cmp_eq_u32 s100, 0
	s_cbranch_scc1 .Lstg_done1
	s_sleep 32
	s_sub_u32 s100, s100, 1
	s_branch .Lstg_loop1
.Lstg_done1:
	s_andn2_b64 vcc, exec, s[4:5]
	v_readfirstlane_b32 s4, v2
	s_cbranch_vccnz .LBB0_862
	s_add_u32 s58, s56, 0x32000000
	v_readlane_b32 s10, v254, 56
	s_addc_u32 s59, s57, 0
	s_lshl_b32 s6, s10, 9
	s_mov_b32 s7, s55
	s_lshl_b64 s[6:7], s[6:7], 2
	v_readlane_b32 s8, v254, 52
	v_readlane_b32 s9, v254, 53
	s_add_u32 s12, s8, s6
	s_addc_u32 s13, s9, s7
	v_readlane_b32 s5, v255, 22
	s_add_u32 s6, s56, s5
	s_mul_i32 s8, s10, 0x600
	s_mov_b32 s9, s55
	v_readlane_b32 s16, v255, 0
	s_addc_u32 s7, s57, s77
	s_lshl_b64 s[8:9], s[8:9], 2
	v_readlane_b32 s18, v255, 2
	v_readlane_b32 s11, v254, 57
	v_readlane_b32 s19, v255, 3
	s_add_u32 s8, s18, s8
	s_addc_u32 s9, s19, s9
	s_lshl_b64 s[10:11], s[54:55], 3
	s_add_u32 s10, s56, s10
	s_addc_u32 s11, s57, s11
	s_ashr_i32 s14, s4, 6
	s_lshl_b32 s60, s14, 4
	s_ashr_i32 s61, s60, 31
	v_bfe_u32 v6, v2, 4, 2
	s_cmp_gt_i32 s14, 3
	v_and_b32_e32 v84, 48, v2
	v_mov_b32_e32 v85, v163
	v_lshlrev_b32_e32 v224, 2, v6
	v_lshlrev_b32_e32 v82, 3, v6
	s_cselect_b64 s[62:63], -1, 0
	v_lshl_add_u64 v[6:7], s[6:7], 0, v[84:85]
	s_lshl_b64 s[6:7], s[60:61], 2
	v_and_b32_e32 v79, 15, v2
	v_and_b32_e32 v9, 63, v2
	s_add_u32 s6, s12, s6
	v_or_b32_e32 v80, s60, v79
	v_mov_b32_e32 v81, s61
	s_addc_u32 s7, s13, s7
	v_lshlrev_b32_e32 v162, 5, v9
	v_lshl_add_u64 v[86:87], s[6:7], 0, v[84:85]
	v_lshl_add_u64 v[88:89], s[8:9], 0, v[162:163]
	s_mov_b64 s[6:7], 0x1000
	v_lshlrev_b64 v[10:11], 8, v[80:81]
	v_lshl_add_u64 v[90:91], v[88:89], 0, s[6:7]
	v_lshl_add_u64 v[6:7], v[6:7], 0, v[10:11]
	s_mov_b64 s[6:7], 0xcd80000
	v_lshl_add_u64 v[92:93], v[6:7], 0, s[6:7]
	s_mov_b64 s[6:7], 0xcd88000
	v_lshl_add_u64 v[94:95], v[6:7], 0, s[6:7]
	s_mov_b64 s[6:7], 0xcd88040
	v_lshl_add_u64 v[96:97], v[6:7], 0, s[6:7]
	s_mov_b64 s[6:7], 0xcd88080
	v_lshl_add_u64 v[98:99], v[6:7], 0, s[6:7]
	s_mov_b64 s[6:7], 0xcd880c0
	v_lshl_add_u64 v[100:101], v[6:7], 0, s[6:7]
	s_mov_b64 s[6:7], 0xcd90000
	v_lshl_add_u64 v[102:103], v[6:7], 0, s[6:7]
	s_mov_b64 s[6:7], 0xcd90040
	v_lshl_add_u64 v[104:105], v[6:7], 0, s[6:7]
	s_mov_b64 s[6:7], 0xcd90080
	v_lshl_add_u64 v[106:107], v[6:7], 0, s[6:7]
	s_mov_b64 s[6:7], 0xcd900c0
	v_lshl_add_u64 v[108:109], v[6:7], 0, s[6:7]
	s_mov_b64 s[6:7], 0xcd98000
	v_lshl_add_u64 v[110:111], v[6:7], 0, s[6:7]
	s_mov_b64 s[6:7], 0xcd98040
	v_lshl_add_u64 v[112:113], v[6:7], 0, s[6:7]
	s_mov_b64 s[6:7], 0xcd98080
	v_lshl_add_u64 v[114:115], v[6:7], 0, s[6:7]
	s_mov_b64 s[6:7], 0xcd980c0
	v_lshl_add_u64 v[116:117], v[6:7], 0, s[6:7]
	s_lshl_b64 s[6:7], s[60:61], 1
	s_add_u32 s6, s56, s6
	v_ashrrev_i32_e32 v3, 31, v2
	v_mov_b32_e32 v83, v163
	s_addc_u32 s7, s57, s7
	v_lshl_add_u64 v[4:5], v[2:3], 3, s[10:11]
	s_mov_b64 s[10:11], 0x100000
	v_lshl_add_u64 v[6:7], s[6:7], 0, v[82:83]
	s_mov_b64 s[6:7], 0x4c000000
	v_lshl_add_u64 v[74:75], v[4:5], 0, s[10:11]
	s_mov_b64 s[10:11], 0x120000
	v_lshlrev_b32_e32 v3, 3, v2
	v_ashrrev_i32_e32 v222, 2, v2
	v_lshl_add_u64 v[118:119], v[6:7], 0, s[6:7]
	v_readlane_b32 s6, v254, 54
	s_movk_i32 s4, 0x80
	v_lshl_add_u64 v[76:77], v[4:5], 0, s[10:11]
	v_and_b32_e32 v4, 0x78, v3
	v_and_b32_e32 v225, -4, v222
	s_movk_i32 s8, 0x110
	v_or_b32_e32 v5, 3, v222
	v_readlane_b32 s7, v254, 55
	v_cmp_gt_i32_e64 s[4:5], s4, v2
	v_add_u32_e32 v121, 0, v3
	v_and_b32_e32 v78, 24, v3
	v_lshlrev_b32_e32 v8, 3, v9
	v_mul_lo_u32 v3, v225, s8
	v_mul_lo_u32 v5, v5, s8
	v_mad_u32_u24 v12, v79, s8, v220
	v_lshl_add_u32 v13, v4, 1, 0
	v_add_u32_e32 v10, 0, v84
	v_and_b32_e32 v2, 3, v2
	v_lshl_add_u64 v[122:123], s[6:7], 0, v[84:85]
	v_readlane_b32 s64, v254, 44
	v_readlane_b32 s6, v254, 42
	v_lshl_add_u32 v223, v222, 3, 0
	v_mul_u32_u24_e32 v226, 0x110, v78
	v_mul_u32_u24_e32 v227, 0x110, v79
	v_mad_u32_u24 v228, v79, s8, v10
	v_lshlrev_b32_e32 v120, 4, v2
	v_lshlrev_b32_e32 v124, 4, v9
	v_mov_b32_e32 v125, v163
	v_lshlrev_b32_e32 v126, 1, v4
	v_lshlrev_b32_e32 v128, 1, v8
	v_add_u32_e32 v83, v13, v3
	v_add_u32_e32 v85, v13, v5
	v_add_u32_e32 v229, v10, v12
	v_readlane_b32 s65, v254, 45
	v_readlane_b32 s61, v254, 37
	s_mov_b32 s41, s6
	v_readlane_b32 s17, v255, 1
	v_readlane_b32 s7, v254, 43
	s_branch .LBB0_760
